# P4 mid-K gate hook: the two half-workgroups now run the hook together (align barrier for half 0 before it, restore barrier for half 1 after it) instead of one after the other; plus peeled first K-iter
# speedup vs baseline: 1.0049x; 1.0049x over previous
.LBB0_489:
	s_cmp_eq_u64 s[18:19], 0
	s_cbranch_scc1 .Lhk4_a
	s_barrier
.Lhk4_a:
	v_mov_b32_e32 v1, v149
	v_mov_b32_e32 v2, v148
	s_mov_b64 s[50:51], 0x8000
	v_add_u32_e32 v2, s90, v2
	v_ashrrev_i32_e32 v3, 31, v2
	v_lshl_add_u32 v136, v1, 3, s91
	v_lshlrev_b64 v[2:3], 11, v[2:3]
	v_lshl_add_u64 v[2:3], s[0:1], 0, v[2:3]
	v_ashrrev_i32_e32 v137, 31, v136
	v_lshl_add_u64 v[2:3], v[2:3], 0, v[136:137]
	global_load_dwordx2 v[140:141], v[2:3], off offset:1024
	global_load_dwordx2 v[136:137], v[2:3], off
	global_load_dwordx2 v[154:155], v[2:3], off offset:1152
	global_load_dwordx2 v[156:157], v[2:3], off offset:128
	v_lshl_add_u64 v[138:139], v[2:3], 0, s[50:51]
	global_load_dwordx2 v[158:159], v[138:139], off offset:1024
	s_mov_b32 s52, 0x8000
	v_add_co_u32_e32 v142, vcc, s52, v2
	s_mov_b64 s[50:51], 0x10000
	s_nop 0
	v_addc_co_u32_e32 v143, vcc, 0, v3, vcc
	global_load_dwordx2 v[166:167], v[142:143], off
	global_load_dwordx2 v[170:171], v[138:139], off offset:1152
	s_nop 0
	global_load_dwordx2 v[142:143], v[138:139], off offset:128
	v_lshl_add_u64 v[160:161], v[2:3], 0, s[50:51]
	global_load_dwordx2 v[138:139], v[160:161], off offset:1024
	s_mov_b32 s50, 0x10000
	s_waitcnt vmcnt(8)
	v_cvt_f32_ubyte2_e32 v185, v141
	v_cvt_f32_ubyte3_e32 v187, v140
	v_cvt_f32_ubyte3_e32 v188, v141
	s_waitcnt vmcnt(6)
	v_cvt_f32_ubyte0_e32 v189, v154
	v_cvt_f32_ubyte1_e32 v191, v154
	v_cvt_f32_ubyte1_e32 v192, v155
	v_cvt_f32_ubyte2_e32 v193, v154
	v_cvt_f32_ubyte3_e32 v195, v154
	v_rcp_iflag_f32_e32 v186, v185
	v_rcp_iflag_f32_e32 v185, v187
	v_rcp_iflag_f32_e32 v187, v188
	v_rcp_iflag_f32_e32 v188, v189
	v_rcp_iflag_f32_e32 v189, v191
	v_rcp_iflag_f32_e32 v191, v192
	v_rcp_iflag_f32_e32 v192, v193
	v_rcp_iflag_f32_e32 v193, v195
	v_cvt_f32_ubyte0_e32 v1, v140
	v_cvt_f32_ubyte0_e32 v162, v141
	v_cvt_f32_ubyte1_e32 v164, v140
	v_cvt_f32_ubyte1_e32 v168, v141
	v_cvt_f32_ubyte2_e32 v184, v140
	v_cvt_f32_ubyte3_e32 v173, v136
	v_cvt_f32_ubyte2_e32 v172, v136
	v_cvt_f32_ubyte1_e32 v175, v136
	v_cvt_f32_ubyte0_e32 v174, v136
	v_cvt_f32_ubyte3_e32 v141, v137
	v_cvt_f32_ubyte2_e32 v140, v137
	v_cvt_f32_ubyte1_e32 v177, v137
	v_cvt_f32_ubyte0_e32 v176, v137
	v_cvt_f32_ubyte2_e32 v194, v155
	s_waitcnt vmcnt(5)
	v_cvt_f32_ubyte3_e32 v137, v156
	v_cvt_f32_ubyte2_e32 v136, v156
	v_cvt_f32_ubyte3_e32 v196, v155
	v_cvt_f32_ubyte1_e32 v179, v156
	v_cvt_f32_ubyte0_e32 v178, v156
	v_rcp_iflag_f32_e32 v156, v1
	v_rcp_iflag_f32_e32 v194, v194
	v_rcp_iflag_f32_e32 v195, v196
	s_waitcnt vmcnt(4)
	v_cvt_f32_ubyte0_e32 v1, v158
	v_pk_mul_f32 v[136:137], v[192:193], v[136:137]
	v_rcp_iflag_f32_e32 v196, v1
	v_pk_mul_f32 v[122:123], v[122:123], v[136:137]
	v_cvt_f32_ubyte1_e32 v1, v158
	v_add_co_u32_e32 v136, vcc, s50, v2
	v_pk_mul_f32 v[140:141], v[186:187], v[140:141]
	v_rcp_iflag_f32_e32 v197, v1
	v_cvt_f32_ubyte1_e32 v1, v159
	v_addc_co_u32_e32 v137, vcc, 0, v3, vcc
	v_cvt_f32_ubyte0_e32 v190, v155
	v_cvt_f32_ubyte3_e32 v155, v157
	v_cvt_f32_ubyte2_e32 v154, v157
	v_pk_mul_f32 v[126:127], v[126:127], v[140:141]
	v_rcp_iflag_f32_e32 v199, v1
	global_load_dwordx2 v[140:141], v[136:137], off
	v_cvt_f32_ubyte2_e32 v1, v158
	v_cvt_f32_ubyte1_e32 v181, v157
	v_cvt_f32_ubyte0_e32 v180, v157
	v_rcp_iflag_f32_e32 v157, v164
	v_pk_mul_f32 v[154:155], v[194:195], v[154:155]
	v_rcp_iflag_f32_e32 v136, v1
	v_cvt_f32_ubyte2_e32 v1, v159
	v_pk_mul_f32 v[118:119], v[118:119], v[154:155]
	v_rcp_iflag_f32_e32 v154, v1
	v_cvt_f32_ubyte3_e32 v1, v158
	v_rcp_iflag_f32_e32 v137, v1
	v_pk_mul_f32 v[156:157], v[156:157], v[174:175]
	v_rcp_iflag_f32_e32 v182, v162
	v_pk_mul_f32 v[128:129], v[128:129], v[156:157]
	s_waitcnt vmcnt(4)
	v_cvt_f32_ubyte3_e32 v157, v166
	v_cvt_f32_ubyte2_e32 v156, v166
	v_pk_mul_f32 v[136:137], v[136:137], v[156:157]
	global_load_dwordx2 v[156:157], v[160:161], off offset:1152
	v_cvt_f32_ubyte0_e32 v162, v159
	v_cvt_f32_ubyte3_e32 v1, v159
	v_rcp_iflag_f32_e32 v198, v162
	v_rcp_iflag_f32_e32 v155, v1
	v_pk_mul_f32 v[114:115], v[114:115], v[136:137]
	v_cvt_f32_ubyte3_e32 v137, v167
	v_cvt_f32_ubyte2_e32 v136, v167
	v_cvt_f32_ubyte1_e32 v159, v167
	v_cvt_f32_ubyte0_e32 v158, v167
	s_waitcnt vmcnt(4)
	v_cvt_f32_ubyte0_e32 v1, v170
	v_rcp_iflag_f32_e32 v184, v184
	v_pk_mul_f32 v[158:159], v[198:199], v[158:159]
	v_pk_mul_f32 v[136:137], v[154:155], v[136:137]
	v_rcp_iflag_f32_e32 v154, v1
	v_cvt_f32_ubyte0_e32 v1, v171
	v_pk_mul_f32 v[110:111], v[110:111], v[136:137]
	v_pk_mul_f32 v[108:109], v[108:109], v[158:159]
	v_rcp_iflag_f32_e32 v158, v1
	v_cvt_f32_ubyte1_e32 v1, v170
	global_load_dwordx2 v[136:137], v[160:161], off offset:128
	v_rcp_iflag_f32_e32 v155, v1
	v_cvt_f32_ubyte1_e32 v1, v171
	v_rcp_iflag_f32_e32 v159, v1
	v_cvt_f32_ubyte2_e32 v1, v170
	v_pk_mul_f32 v[172:173], v[184:185], v[172:173]
	v_rcp_iflag_f32_e32 v160, v1
	v_cvt_f32_ubyte2_e32 v1, v171
	v_pk_mul_f32 v[130:131], v[130:131], v[172:173]
	v_cvt_f32_ubyte1_e32 v173, v166
	v_cvt_f32_ubyte0_e32 v172, v166
	v_rcp_iflag_f32_e32 v166, v1
	v_cvt_f32_ubyte3_e32 v1, v170
	v_rcp_iflag_f32_e32 v161, v1
	v_pk_mul_f32 v[172:173], v[196:197], v[172:173]
	v_cvt_f32_ubyte3_e32 v1, v171
	v_pk_mul_f32 v[112:113], v[112:113], v[172:173]
	s_waitcnt vmcnt(4)
	v_cvt_f32_ubyte3_e32 v173, v142
	v_cvt_f32_ubyte2_e32 v172, v142
	v_lshl_add_u64 v[170:171], v[2:3], 0, s[20:21]
	v_rcp_iflag_f32_e32 v183, v168
	v_pk_mul_f32 v[160:161], v[160:161], v[172:173]
	global_load_dwordx2 v[172:173], v[170:171], off offset:1024
	v_pk_mul_f32 v[106:107], v[106:107], v[160:161]
	v_pk_mul_f32 v[174:175], v[182:183], v[176:177]
	v_cvt_f32_ubyte1_e32 v161, v143
	v_pk_mul_f32 v[124:125], v[124:125], v[174:175]
	v_cvt_f32_ubyte1_e32 v175, v142
	v_cvt_f32_ubyte0_e32 v174, v142
	v_pk_mul_f32 v[154:155], v[154:155], v[174:175]
	v_cvt_f32_ubyte0_e32 v160, v143
	v_pk_mul_f32 v[104:105], v[104:105], v[154:155]
	v_cvt_f32_ubyte3_e32 v155, v143
	v_cvt_f32_ubyte2_e32 v154, v143
	v_pk_mul_f32 v[142:143], v[158:159], v[160:161]
	s_mov_b32 s50, 0x18000
	v_pk_mul_f32 v[100:101], v[100:101], v[142:143]
	v_add_co_u32_e32 v142, vcc, s50, v2
	v_rcp_iflag_f32_e32 v167, v1
	s_nop 0
	v_addc_co_u32_e32 v143, vcc, 0, v3, vcc
	global_load_dwordx2 v[142:143], v[142:143], off
	v_pk_mul_f32 v[154:155], v[166:167], v[154:155]
	s_waitcnt vmcnt(5)
	v_cvt_f32_ubyte0_e32 v1, v138
	v_pk_mul_f32 v[102:103], v[102:103], v[154:155]
	v_rcp_iflag_f32_e32 v154, v1
	v_cvt_f32_ubyte0_e32 v1, v139
	v_rcp_iflag_f32_e32 v158, v1
	v_cvt_f32_ubyte1_e32 v1, v138
	v_rcp_iflag_f32_e32 v155, v1
	v_cvt_f32_ubyte1_e32 v1, v139
	v_rcp_iflag_f32_e32 v159, v1
	v_cvt_f32_ubyte2_e32 v1, v138
	v_rcp_iflag_f32_e32 v160, v1
	v_cvt_f32_ubyte2_e32 v1, v139
	v_rcp_iflag_f32_e32 v166, v1
	v_cvt_f32_ubyte3_e32 v1, v138
	v_rcp_iflag_f32_e32 v161, v1
	s_waitcnt vmcnt(4)
	v_cvt_f32_ubyte3_e32 v175, v140
	v_cvt_f32_ubyte2_e32 v174, v140
	v_cvt_f32_ubyte3_e32 v1, v139
	v_pk_mul_f32 v[160:161], v[160:161], v[174:175]
	v_rcp_iflag_f32_e32 v167, v1
	v_pk_mul_f32 v[98:99], v[98:99], v[160:161]
	global_load_dwordx2 v[160:161], v[170:171], off offset:1152
	v_pk_mul_f32 v[176:177], v[188:189], v[178:179]
	v_cvt_f32_ubyte3_e32 v139, v141
	v_pk_mul_f32 v[120:121], v[120:121], v[176:177]
	v_cvt_f32_ubyte1_e32 v177, v140
	v_cvt_f32_ubyte0_e32 v176, v140
	v_cvt_f32_ubyte2_e32 v138, v141
	v_pk_mul_f32 v[154:155], v[154:155], v[176:177]
	v_pk_mul_f32 v[138:139], v[166:167], v[138:139]
	s_waitcnt vmcnt(4)
	v_cvt_f32_ubyte0_e32 v1, v156
	v_pk_mul_f32 v[96:97], v[96:97], v[154:155]
	v_cvt_f32_ubyte1_e32 v155, v141
	v_cvt_f32_ubyte0_e32 v154, v141
	v_pk_mul_f32 v[94:95], v[94:95], v[138:139]
	v_rcp_iflag_f32_e32 v138, v1
	v_cvt_f32_ubyte0_e32 v1, v157
	v_pk_mul_f32 v[140:141], v[158:159], v[154:155]
	v_rcp_iflag_f32_e32 v154, v1
	v_cvt_f32_ubyte1_e32 v1, v156
	v_rcp_iflag_f32_e32 v139, v1
	v_cvt_f32_ubyte1_e32 v1, v157
	v_rcp_iflag_f32_e32 v155, v1
	v_cvt_f32_ubyte2_e32 v1, v156
	v_pk_mul_f32 v[92:93], v[92:93], v[140:141]
	global_load_dwordx2 v[140:141], v[170:171], off offset:128
	v_rcp_iflag_f32_e32 v158, v1
	v_cvt_f32_ubyte2_e32 v1, v157
	v_rcp_iflag_f32_e32 v166, v1
	v_cvt_f32_ubyte3_e32 v1, v156
	v_rcp_iflag_f32_e32 v159, v1
	s_waitcnt vmcnt(4)
	v_cvt_f32_ubyte3_e32 v171, v136
	v_cvt_f32_ubyte2_e32 v170, v136
	v_cvt_f32_ubyte3_e32 v1, v157
	v_pk_mul_f32 v[158:159], v[158:159], v[170:171]
	v_lshl_add_u64 v[156:157], v[2:3], 0, s[14:15]
	v_pk_mul_f32 v[90:91], v[90:91], v[158:159]
	global_load_dwordx2 v[158:159], v[156:157], off offset:1024
	v_rcp_iflag_f32_e32 v167, v1
	v_cvt_f32_ubyte1_e32 v175, v136
	v_cvt_f32_ubyte0_e32 v174, v136
	v_pk_mul_f32 v[138:139], v[138:139], v[174:175]
	v_cvt_f32_ubyte1_e32 v171, v137
	v_cvt_f32_ubyte0_e32 v170, v137
	v_pk_mul_f32 v[88:89], v[88:89], v[138:139]
	v_cvt_f32_ubyte3_e32 v139, v137
	v_cvt_f32_ubyte2_e32 v138, v137
	v_pk_mul_f32 v[136:137], v[154:155], v[170:171]
	v_pk_mul_f32 v[138:139], v[166:167], v[138:139]
	v_pk_mul_f32 v[84:85], v[84:85], v[136:137]
	s_waitcnt vmcnt(4)
	v_cvt_f32_ubyte0_e32 v1, v172
	v_add_co_u32_e32 v136, vcc, s81, v2
	v_pk_mul_f32 v[86:87], v[86:87], v[138:139]
	v_rcp_iflag_f32_e32 v138, v1
	v_cvt_f32_ubyte0_e32 v1, v173
	v_addc_co_u32_e32 v137, vcc, 0, v3, vcc
	v_rcp_iflag_f32_e32 v154, v1
	v_cvt_f32_ubyte1_e32 v1, v172
	global_load_dwordx2 v[136:137], v[136:137], off
	v_rcp_iflag_f32_e32 v139, v1
	v_cvt_f32_ubyte1_e32 v1, v173
	v_rcp_iflag_f32_e32 v155, v1
	v_cvt_f32_ubyte2_e32 v1, v172
	v_rcp_iflag_f32_e32 v166, v1
	v_cvt_f32_ubyte2_e32 v1, v173
	v_rcp_iflag_f32_e32 v170, v1
	v_cvt_f32_ubyte3_e32 v1, v172
	v_rcp_iflag_f32_e32 v167, v1
	s_waitcnt vmcnt(4)
	v_cvt_f32_ubyte3_e32 v175, v142
	v_cvt_f32_ubyte2_e32 v174, v142
	v_cvt_f32_ubyte3_e32 v1, v173
	v_pk_mul_f32 v[166:167], v[166:167], v[174:175]
	v_rcp_iflag_f32_e32 v171, v1
	v_pk_mul_f32 v[82:83], v[82:83], v[166:167]
	global_load_dwordx2 v[166:167], v[156:157], off offset:1152
	v_cvt_f32_ubyte1_e32 v177, v142
	v_cvt_f32_ubyte0_e32 v176, v142
	v_pk_mul_f32 v[138:139], v[138:139], v[176:177]
	v_cvt_f32_ubyte1_e32 v173, v143
	v_pk_mul_f32 v[80:81], v[80:81], v[138:139]
	v_cvt_f32_ubyte3_e32 v139, v143
	v_cvt_f32_ubyte2_e32 v138, v143
	v_pk_mul_f32 v[138:139], v[170:171], v[138:139]
	v_cvt_f32_ubyte0_e32 v172, v143
	v_pk_mul_f32 v[78:79], v[78:79], v[138:139]
	global_load_dwordx2 v[138:139], v[156:157], off offset:128
	v_pk_mul_f32 v[142:143], v[154:155], v[172:173]
	s_waitcnt vmcnt(5)
	v_cvt_f32_ubyte0_e32 v1, v160
	v_pk_mul_f32 v[76:77], v[76:77], v[142:143]
	v_rcp_iflag_f32_e32 v142, v1
	v_cvt_f32_ubyte0_e32 v1, v161
	v_rcp_iflag_f32_e32 v154, v1
	v_cvt_f32_ubyte1_e32 v1, v160
	v_rcp_iflag_f32_e32 v143, v1
	v_cvt_f32_ubyte1_e32 v1, v161
	v_rcp_iflag_f32_e32 v155, v1
	v_cvt_f32_ubyte2_e32 v1, v160
	v_rcp_iflag_f32_e32 v156, v1
	v_cvt_f32_ubyte2_e32 v1, v161
	v_rcp_iflag_f32_e32 v170, v1
	v_cvt_f32_ubyte3_e32 v1, v160
	v_rcp_iflag_f32_e32 v157, v1
	s_waitcnt vmcnt(4)
	v_cvt_f32_ubyte3_e32 v173, v140
	v_cvt_f32_ubyte2_e32 v172, v140
	v_cvt_f32_ubyte3_e32 v1, v161
	v_lshl_add_u64 v[160:161], v[2:3], 0, s[22:23]
	v_pk_mul_f32 v[156:157], v[156:157], v[172:173]
	global_load_dwordx2 v[172:173], v[160:161], off offset:1024
	v_rcp_iflag_f32_e32 v171, v1
	v_cvt_f32_ubyte1_e32 v175, v140
	v_cvt_f32_ubyte0_e32 v174, v140
	v_pk_mul_f32 v[142:143], v[142:143], v[174:175]
	v_pk_mul_f32 v[74:75], v[74:75], v[156:157]
	v_cvt_f32_ubyte1_e32 v157, v141
	v_cvt_f32_ubyte0_e32 v156, v141
	v_pk_mul_f32 v[72:73], v[72:73], v[142:143]
	v_cvt_f32_ubyte3_e32 v143, v141
	v_cvt_f32_ubyte2_e32 v142, v141
	v_pk_mul_f32 v[140:141], v[154:155], v[156:157]
	s_waitcnt vmcnt(4)
	v_cvt_f32_ubyte0_e32 v1, v158
	v_pk_mul_f32 v[142:143], v[170:171], v[142:143]
	v_pk_mul_f32 v[68:69], v[68:69], v[140:141]
	v_rcp_iflag_f32_e32 v140, v1
	v_cvt_f32_ubyte0_e32 v1, v159
	v_pk_mul_f32 v[70:71], v[70:71], v[142:143]
	v_rcp_iflag_f32_e32 v154, v1
	v_cvt_f32_ubyte1_e32 v1, v158
	v_add_co_u32_e32 v142, vcc, s82, v2
	v_rcp_iflag_f32_e32 v141, v1
	v_cvt_f32_ubyte1_e32 v1, v159
	v_addc_co_u32_e32 v143, vcc, 0, v3, vcc
	v_rcp_iflag_f32_e32 v155, v1
	v_cvt_f32_ubyte2_e32 v1, v158
	global_load_dwordx2 v[142:143], v[142:143], off
	v_rcp_iflag_f32_e32 v156, v1
	v_cvt_f32_ubyte2_e32 v1, v159
	v_rcp_iflag_f32_e32 v170, v1
	v_cvt_f32_ubyte3_e32 v1, v158
	v_rcp_iflag_f32_e32 v157, v1
	v_cvt_f32_ubyte3_e32 v1, v159
	global_load_dwordx2 v[158:159], v[160:161], off offset:1152
	v_rcp_iflag_f32_e32 v171, v1
	s_waitcnt vmcnt(5)
	v_cvt_f32_ubyte1_e32 v177, v136
	v_cvt_f32_ubyte0_e32 v176, v136
	v_pk_mul_f32 v[140:141], v[140:141], v[176:177]
	v_cvt_f32_ubyte3_e32 v175, v136
	v_pk_mul_f32 v[64:65], v[64:65], v[140:141]
	v_cvt_f32_ubyte3_e32 v141, v137
	v_cvt_f32_ubyte2_e32 v140, v137
	v_pk_mul_f32 v[140:141], v[170:171], v[140:141]
	v_cvt_f32_ubyte2_e32 v174, v136
	v_pk_mul_f32 v[62:63], v[62:63], v[140:141]
	global_load_dwordx2 v[140:141], v[160:161], off offset:128
	v_pk_mul_f32 v[156:157], v[156:157], v[174:175]
	s_waitcnt vmcnt(5)
	v_cvt_f32_ubyte0_e32 v1, v166
	v_pk_mul_f32 v[66:67], v[66:67], v[156:157]
	v_cvt_f32_ubyte1_e32 v157, v137
	v_cvt_f32_ubyte0_e32 v156, v137
	v_pk_mul_f32 v[136:137], v[154:155], v[156:157]
	v_rcp_iflag_f32_e32 v190, v190
	v_pk_mul_f32 v[60:61], v[60:61], v[136:137]
	v_rcp_iflag_f32_e32 v136, v1
	v_cvt_f32_ubyte0_e32 v1, v167
	v_rcp_iflag_f32_e32 v154, v1
	v_cvt_f32_ubyte1_e32 v1, v166
	v_rcp_iflag_f32_e32 v137, v1
	v_cvt_f32_ubyte1_e32 v1, v167
	v_rcp_iflag_f32_e32 v155, v1
	v_cvt_f32_ubyte2_e32 v1, v166
	v_rcp_iflag_f32_e32 v156, v1
	v_cvt_f32_ubyte2_e32 v1, v167
	v_rcp_iflag_f32_e32 v160, v1
	v_cvt_f32_ubyte3_e32 v1, v166
	s_waitcnt vmcnt(4)
	v_cvt_f32_ubyte1_e32 v175, v138
	v_cvt_f32_ubyte0_e32 v174, v138
	v_rcp_iflag_f32_e32 v157, v1
	v_pk_mul_f32 v[136:137], v[136:137], v[174:175]
	v_cvt_f32_ubyte3_e32 v1, v167
	v_lshl_add_u64 v[166:167], v[2:3], 0, s[24:25]
	v_pk_mul_f32 v[56:57], v[56:57], v[136:137]
	global_load_dwordx2 v[136:137], v[166:167], off offset:1024
	v_cvt_f32_ubyte3_e32 v171, v138
	v_cvt_f32_ubyte2_e32 v170, v138
	v_pk_mul_f32 v[156:157], v[156:157], v[170:171]
	v_cvt_f32_ubyte1_e32 v171, v139
	v_cvt_f32_ubyte0_e32 v170, v139
	v_pk_mul_f32 v[58:59], v[58:59], v[156:157]
	v_cvt_f32_ubyte3_e32 v157, v139
	v_cvt_f32_ubyte2_e32 v156, v139
	v_pk_mul_f32 v[138:139], v[154:155], v[170:171]
	v_rcp_iflag_f32_e32 v161, v1
	v_pk_mul_f32 v[52:53], v[52:53], v[138:139]
	v_add_co_u32_e32 v138, vcc, s83, v2
	v_pk_mul_f32 v[154:155], v[160:161], v[156:157]
	s_nop 0
	v_addc_co_u32_e32 v139, vcc, 0, v3, vcc
	global_load_dwordx2 v[138:139], v[138:139], off
	s_waitcnt vmcnt(5)
	v_cvt_f32_ubyte0_e32 v1, v172
	v_pk_mul_f32 v[54:55], v[54:55], v[154:155]
	v_rcp_iflag_f32_e32 v154, v1
	v_cvt_f32_ubyte0_e32 v1, v173
	v_rcp_iflag_f32_e32 v156, v1
	v_cvt_f32_ubyte1_e32 v1, v172
	v_rcp_iflag_f32_e32 v155, v1
	v_cvt_f32_ubyte1_e32 v1, v173
	v_rcp_iflag_f32_e32 v157, v1
	v_cvt_f32_ubyte2_e32 v1, v172
	v_rcp_iflag_f32_e32 v160, v1
	v_cvt_f32_ubyte2_e32 v1, v173
	v_rcp_iflag_f32_e32 v170, v1
	v_cvt_f32_ubyte3_e32 v1, v172
	v_rcp_iflag_f32_e32 v161, v1
	v_cvt_f32_ubyte3_e32 v1, v173
	s_waitcnt vmcnt(4)
	v_cvt_f32_ubyte3_e32 v175, v142
	v_cvt_f32_ubyte2_e32 v174, v142
	v_rcp_iflag_f32_e32 v171, v1
	v_cvt_f32_ubyte1_e32 v177, v142
	v_cvt_f32_ubyte0_e32 v176, v142
	v_pk_mul_f32 v[160:161], v[160:161], v[174:175]
	global_load_dwordx2 v[172:173], v[166:167], off offset:1152
	v_pk_mul_f32 v[154:155], v[154:155], v[176:177]
	v_pk_mul_f32 v[50:51], v[50:51], v[160:161]
	v_cvt_f32_ubyte1_e32 v161, v143
	v_cvt_f32_ubyte0_e32 v160, v143
	v_pk_mul_f32 v[48:49], v[48:49], v[154:155]
	v_cvt_f32_ubyte3_e32 v155, v143
	v_cvt_f32_ubyte2_e32 v154, v143
	v_pk_mul_f32 v[142:143], v[156:157], v[160:161]
	s_waitcnt vmcnt(4)
	v_cvt_f32_ubyte0_e32 v1, v158
	v_pk_mul_f32 v[154:155], v[170:171], v[154:155]
	v_pk_mul_f32 v[44:45], v[44:45], v[142:143]
	v_rcp_iflag_f32_e32 v142, v1
	v_cvt_f32_ubyte0_e32 v1, v159
	v_pk_mul_f32 v[46:47], v[46:47], v[154:155]
	v_rcp_iflag_f32_e32 v154, v1
	v_cvt_f32_ubyte1_e32 v1, v158
	v_rcp_iflag_f32_e32 v143, v1
	v_cvt_f32_ubyte1_e32 v1, v159
	s_waitcnt vmcnt(3)
	v_cvt_f32_ubyte1_e32 v175, v140
	v_cvt_f32_ubyte0_e32 v174, v140
	v_rcp_iflag_f32_e32 v155, v1
	global_load_dwordx2 v[156:157], v[166:167], off offset:128
	v_cvt_f32_ubyte2_e32 v1, v158
	v_pk_mul_f32 v[142:143], v[142:143], v[174:175]
	v_rcp_iflag_f32_e32 v160, v1
	v_cvt_f32_ubyte2_e32 v1, v159
	v_pk_mul_f32 v[40:41], v[40:41], v[142:143]
	v_lshl_add_u64 v[142:143], v[2:3], 0, s[26:27]
	global_load_dwordx2 v[176:177], v[142:143], off offset:1152
	v_rcp_iflag_f32_e32 v166, v1
	v_cvt_f32_ubyte3_e32 v1, v158
	v_rcp_iflag_f32_e32 v161, v1
	v_cvt_f32_ubyte3_e32 v1, v159
	global_load_dwordx2 v[158:159], v[142:143], off offset:1024
	v_rcp_iflag_f32_e32 v167, v1
	v_cvt_f32_ubyte3_e32 v171, v140
	v_cvt_f32_ubyte2_e32 v170, v140
	v_add_co_u32_e32 v2, vcc, s84, v2
	v_pk_mul_f32 v[160:161], v[160:161], v[170:171]
	v_cvt_f32_ubyte1_e32 v171, v141
	v_cvt_f32_ubyte0_e32 v170, v141
	v_addc_co_u32_e32 v3, vcc, 0, v3, vcc
	v_pk_mul_f32 v[42:43], v[42:43], v[160:161]
	v_cvt_f32_ubyte3_e32 v161, v141
	v_cvt_f32_ubyte2_e32 v160, v141
	v_pk_mul_f32 v[140:141], v[154:155], v[170:171]
	s_waitcnt vmcnt(5)
	v_cvt_f32_ubyte0_e32 v1, v136
	global_load_dwordx2 v[2:3], v[2:3], off
	v_pk_mul_f32 v[154:155], v[166:167], v[160:161]
	v_pk_mul_f32 v[36:37], v[36:37], v[140:141]
	v_rcp_iflag_f32_e32 v140, v1
	v_cvt_f32_ubyte0_e32 v1, v137
	v_pk_mul_f32 v[38:39], v[38:39], v[154:155]
	v_rcp_iflag_f32_e32 v154, v1
	v_cvt_f32_ubyte1_e32 v1, v136
	v_rcp_iflag_f32_e32 v141, v1
	v_cvt_f32_ubyte1_e32 v1, v137
	v_rcp_iflag_f32_e32 v155, v1
	v_cvt_f32_ubyte2_e32 v1, v136
	v_rcp_iflag_f32_e32 v160, v1
	v_cvt_f32_ubyte2_e32 v1, v137
	v_rcp_iflag_f32_e32 v166, v1
	v_cvt_f32_ubyte3_e32 v1, v136
	v_rcp_iflag_f32_e32 v161, v1
	v_cvt_f32_ubyte3_e32 v1, v137
	v_rcp_iflag_f32_e32 v167, v1
	s_waitcnt vmcnt(5)
	v_cvt_f32_ubyte3_e32 v137, v139
	v_cvt_f32_ubyte2_e32 v136, v139
	v_cvt_f32_ubyte1_e32 v175, v138
	v_pk_mul_f32 v[136:137], v[166:167], v[136:137]
	v_cvt_f32_ubyte0_e32 v174, v138
	v_pk_mul_f32 v[30:31], v[30:31], v[136:137]
	global_load_dwordx2 v[136:137], v[142:143], off offset:128
	v_pk_mul_f32 v[140:141], v[140:141], v[174:175]
	v_cvt_f32_ubyte3_e32 v171, v138
	v_pk_mul_f32 v[32:33], v[32:33], v[140:141]
	v_cvt_f32_ubyte1_e32 v141, v139
	v_cvt_f32_ubyte0_e32 v140, v139
	v_cvt_f32_ubyte2_e32 v170, v138
	v_pk_mul_f32 v[138:139], v[154:155], v[140:141]
	s_waitcnt vmcnt(5)
	v_cvt_f32_ubyte0_e32 v1, v172
	v_pk_mul_f32 v[28:29], v[28:29], v[138:139]
	v_rcp_iflag_f32_e32 v138, v1
	v_cvt_f32_ubyte0_e32 v1, v173
	v_rcp_iflag_f32_e32 v140, v1
	v_cvt_f32_ubyte1_e32 v1, v172
	v_rcp_iflag_f32_e32 v139, v1
	v_cvt_f32_ubyte1_e32 v1, v173
	v_rcp_iflag_f32_e32 v141, v1
	v_cvt_f32_ubyte2_e32 v1, v172
	v_rcp_iflag_f32_e32 v142, v1
	v_cvt_f32_ubyte2_e32 v1, v173
	v_rcp_iflag_f32_e32 v154, v1
	v_cvt_f32_ubyte3_e32 v1, v172
	v_rcp_iflag_f32_e32 v143, v1
	v_cvt_f32_ubyte3_e32 v1, v173
	v_rcp_iflag_f32_e32 v155, v1
	v_pk_mul_f32 v[160:161], v[160:161], v[170:171]
	s_waitcnt vmcnt(4)
	v_cvt_f32_ubyte1_e32 v167, v156
	v_cvt_f32_ubyte0_e32 v166, v156
	v_pk_mul_f32 v[34:35], v[34:35], v[160:161]
	v_cvt_f32_ubyte3_e32 v161, v156
	v_cvt_f32_ubyte2_e32 v160, v156
	v_pk_mul_f32 v[138:139], v[138:139], v[166:167]
	v_pk_mul_f32 v[142:143], v[142:143], v[160:161]
	v_pk_mul_f32 v[24:25], v[24:25], v[138:139]
	v_cvt_f32_ubyte3_e32 v139, v157
	v_cvt_f32_ubyte2_e32 v138, v157
	v_pk_mul_f32 v[26:27], v[26:27], v[142:143]
	v_cvt_f32_ubyte1_e32 v143, v157
	v_cvt_f32_ubyte0_e32 v142, v157
	v_pk_mul_f32 v[138:139], v[154:155], v[138:139]
	s_waitcnt vmcnt(2)
	v_cvt_f32_ubyte0_e32 v1, v158
	v_pk_mul_f32 v[140:141], v[140:141], v[142:143]
	v_pk_mul_f32 v[22:23], v[22:23], v[138:139]
	v_rcp_iflag_f32_e32 v138, v1
	v_cvt_f32_ubyte0_e32 v1, v159
	v_pk_mul_f32 v[20:21], v[20:21], v[140:141]
	v_rcp_iflag_f32_e32 v140, v1
	v_cvt_f32_ubyte1_e32 v1, v158
	v_rcp_iflag_f32_e32 v139, v1
	v_cvt_f32_ubyte1_e32 v1, v159
	v_rcp_iflag_f32_e32 v141, v1
	v_cvt_f32_ubyte2_e32 v1, v158
	v_rcp_iflag_f32_e32 v142, v1
	v_cvt_f32_ubyte2_e32 v1, v159
	v_rcp_iflag_f32_e32 v154, v1
	v_cvt_f32_ubyte3_e32 v1, v158
	v_rcp_iflag_f32_e32 v143, v1
	v_cvt_f32_ubyte3_e32 v1, v159
	s_waitcnt vmcnt(1)
	v_cvt_f32_ubyte3_e32 v157, v2
	v_cvt_f32_ubyte2_e32 v156, v2
	v_rcp_iflag_f32_e32 v155, v1
	v_cvt_f32_ubyte1_e32 v161, v2
	v_cvt_f32_ubyte0_e32 v160, v2
	v_pk_mul_f32 v[142:143], v[142:143], v[156:157]
	v_pk_mul_f32 v[138:139], v[138:139], v[160:161]
	v_pk_mul_f32 v[18:19], v[18:19], v[142:143]
	v_cvt_f32_ubyte1_e32 v143, v3
	v_cvt_f32_ubyte0_e32 v142, v3
	v_pk_mul_f32 v[16:17], v[16:17], v[138:139]
	v_cvt_f32_ubyte3_e32 v139, v3
	v_cvt_f32_ubyte2_e32 v138, v3
	v_pk_mul_f32 v[2:3], v[140:141], v[142:143]
	v_cvt_f32_ubyte0_e32 v1, v176
	v_pk_mul_f32 v[138:139], v[154:155], v[138:139]
	v_pk_mul_f32 v[12:13], v[12:13], v[2:3]
	v_rcp_iflag_f32_e32 v2, v1
	v_cvt_f32_ubyte0_e32 v1, v177
	v_pk_mul_f32 v[14:15], v[14:15], v[138:139]
	v_rcp_iflag_f32_e32 v138, v1
	v_cvt_f32_ubyte1_e32 v1, v176
	v_rcp_iflag_f32_e32 v3, v1
	v_cvt_f32_ubyte1_e32 v1, v177
	v_rcp_iflag_f32_e32 v139, v1
	v_cvt_f32_ubyte2_e32 v1, v176
	v_rcp_iflag_f32_e32 v140, v1
	v_cvt_f32_ubyte2_e32 v1, v177
	v_rcp_iflag_f32_e32 v142, v1
	v_cvt_f32_ubyte3_e32 v1, v176
	v_rcp_iflag_f32_e32 v141, v1
	v_cvt_f32_ubyte3_e32 v1, v177
	v_rcp_iflag_f32_e32 v143, v1
	s_waitcnt vmcnt(0)
	v_cvt_f32_ubyte3_e32 v155, v136
	v_cvt_f32_ubyte2_e32 v154, v136
	v_cvt_f32_ubyte1_e32 v157, v136
	v_cvt_f32_ubyte0_e32 v156, v136
	v_pk_mul_f32 v[2:3], v[2:3], v[156:157]
	v_pk_mul_f32 v[140:141], v[140:141], v[154:155]
	v_pk_mul_f32 v[8:9], v[8:9], v[2:3]
	v_pk_mul_f32 v[10:11], v[10:11], v[140:141]
	v_cvt_f32_ubyte3_e32 v3, v137
	v_cvt_f32_ubyte2_e32 v2, v137
	v_cvt_f32_ubyte1_e32 v141, v137
	v_cvt_f32_ubyte0_e32 v140, v137
	v_pk_mul_f32 v[178:179], v[190:191], v[180:181]
	v_pk_mul_f32 v[136:137], v[138:139], v[140:141]
	v_pk_mul_f32 v[2:3], v[142:143], v[2:3]
	v_pk_mul_f32 v[116:117], v[116:117], v[178:179]
	v_pk_mul_f32 v[6:7], v[6:7], v[2:3]
	v_pk_mul_f32 v[4:5], v[4:5], v[136:137]
	s_cmp_eq_u64 s[18:19], 0
	s_cbranch_scc0 .Lhk4_b
	s_barrier
.Lhk4_b:
.LBB0_490:
	v_add_u32_e32 v1, 0x10000, v152
	ds_read_b128 v[136:139], v1
	ds_read_b128 v[140:143], v1 offset:1024
	ds_read_b128 v[154:157], v1 offset:2048
	ds_read_b128 v[158:161], v1 offset:3072
	v_add_u32_e32 v1, 0x14000, v152
	s_add_u32 s50, s44, 0x100
	ds_read_b128 v[170:173], v1
	ds_read_b128 v[174:177], v1 offset:1024
	ds_read_b128 v[178:181], v1 offset:2048
	ds_read_b128 v[182:185], v1 offset:3072
	s_addc_u32 s51, s45, 0
	s_cmp_eq_u32 s94, 12
	s_cselect_b32 s58, s85, s50
	s_cselect_b32 s59, s35, s51
	s_cselect_b32 s53, s87, s93
	s_cselect_b32 s52, s88, s92
	s_add_u32 s54, s58, 0x80
	s_addc_u32 s55, s59, 0
	s_add_u32 s56, s52, 0x80
	s_addc_u32 s57, s53, 0
	ds_read_b128 v[186:189], v153
	ds_read_b128 v[190:193], v153 offset:1024
	ds_read_b128 v[194:197], v153 offset:2048
	ds_read_b128 v[198:201], v153 offset:3072
	ds_read_b128 v[202:205], v153 offset:4096
	ds_read_b128 v[206:209], v153 offset:5120
	ds_read_b128 v[210:213], v153 offset:6144
	ds_read_b128 v[214:217], v153 offset:7168
	s_add_u32 s44, s44, 0x40080
	s_addc_u32 s45, s45, 0
	s_mov_b32 s95, m0
	s_mov_b32 m0, s78
	s_nop 0
	global_load_lds_dwordx4 v144, s[44:45]
	s_mov_b32 m0, s95
	s_add_i32 s95, s40, 0xe000
	s_mov_b32 s96, m0
	s_mov_b32 m0, s95
	s_nop 0
	global_load_lds_dwordx4 v146, s[44:45]
	s_mov_b32 m0, s96
	s_waitcnt vmcnt(8)
	s_waitcnt lgkmcnt(0)
	s_barrier
	s_setprio 1
	s_waitcnt lgkmcnt(7)
	v_mfma_f32_16x16x32_bf16 v[128:131], v[136:139], v[186:189], v[128:131]
	v_mfma_f32_16x16x32_bf16 v[124:127], v[154:157], v[186:189], v[124:127]
	s_waitcnt lgkmcnt(5)
	v_mfma_f32_16x16x32_bf16 v[112:115], v[136:139], v[194:197], v[112:115]
	v_mfma_f32_16x16x32_bf16 v[108:111], v[154:157], v[194:197], v[108:111]
	s_waitcnt lgkmcnt(3)
	v_mfma_f32_16x16x32_bf16 v[96:99], v[136:139], v[202:205], v[96:99]
	v_mfma_f32_16x16x32_bf16 v[92:95], v[154:157], v[202:205], v[92:95]
	s_waitcnt lgkmcnt(1)
	v_mfma_f32_16x16x32_bf16 v[80:83], v[136:139], v[210:213], v[80:83]
	v_mfma_f32_16x16x32_bf16 v[76:79], v[154:157], v[210:213], v[76:79]
	v_mfma_f32_16x16x32_bf16 v[128:131], v[140:143], v[190:193], v[128:131]
	v_mfma_f32_16x16x32_bf16 v[124:127], v[158:161], v[190:193], v[124:127]
	v_mfma_f32_16x16x32_bf16 v[112:115], v[140:143], v[198:201], v[112:115]
	v_mfma_f32_16x16x32_bf16 v[108:111], v[158:161], v[198:201], v[108:111]
	v_mfma_f32_16x16x32_bf16 v[96:99], v[140:143], v[206:209], v[96:99]
	v_mfma_f32_16x16x32_bf16 v[92:95], v[158:161], v[206:209], v[92:95]
	s_waitcnt lgkmcnt(0)
	v_mfma_f32_16x16x32_bf16 v[80:83], v[140:143], v[214:217], v[80:83]
	v_mfma_f32_16x16x32_bf16 v[76:79], v[158:161], v[214:217], v[76:79]
	s_setprio 0
	s_setprio 1
	v_mfma_f32_16x16x32_bf16 v[120:123], v[170:173], v[186:189], v[120:123]
	v_mfma_f32_16x16x32_bf16 v[116:119], v[178:181], v[186:189], v[116:119]
	v_mfma_f32_16x16x32_bf16 v[104:107], v[170:173], v[194:197], v[104:107]
	v_mfma_f32_16x16x32_bf16 v[100:103], v[178:181], v[194:197], v[100:103]
	v_mfma_f32_16x16x32_bf16 v[88:91], v[170:173], v[202:205], v[88:91]
	v_mfma_f32_16x16x32_bf16 v[84:87], v[178:181], v[202:205], v[84:87]
	v_mfma_f32_16x16x32_bf16 v[72:75], v[170:173], v[210:213], v[72:75]
	v_mfma_f32_16x16x32_bf16 v[68:71], v[178:181], v[210:213], v[68:71]
	v_mfma_f32_16x16x32_bf16 v[120:123], v[174:177], v[190:193], v[120:123]
	v_mfma_f32_16x16x32_bf16 v[116:119], v[182:185], v[190:193], v[116:119]
	v_mfma_f32_16x16x32_bf16 v[104:107], v[174:177], v[198:201], v[104:107]
	v_mfma_f32_16x16x32_bf16 v[100:103], v[182:185], v[198:201], v[100:103]
	v_mfma_f32_16x16x32_bf16 v[88:91], v[174:177], v[206:209], v[88:91]
	v_mfma_f32_16x16x32_bf16 v[84:87], v[182:185], v[206:209], v[84:87]
	v_mfma_f32_16x16x32_bf16 v[72:75], v[174:177], v[214:217], v[72:75]
	v_mfma_f32_16x16x32_bf16 v[68:71], v[182:185], v[214:217], v[68:71]
	s_setprio 0
	s_barrier
	ds_read_b128 v[186:189], v153 offset:16384
	ds_read_b128 v[190:193], v153 offset:17408
	ds_read_b128 v[194:197], v153 offset:18432
	ds_read_b128 v[198:201], v153 offset:19456
	ds_read_b128 v[202:205], v153 offset:20480
	ds_read_b128 v[206:209], v153 offset:21504
	ds_read_b128 v[210:213], v153 offset:22528
	ds_read_b128 v[214:217], v153 offset:23552
	s_mov_b32 s44, m0
	s_mov_b32 m0, s41
	s_nop 0
	global_load_lds_dwordx4 v145, s[52:53]
	s_mov_b32 m0, s44
	s_nop 0
	s_mov_b32 s44, m0
	s_mov_b32 m0, s60
	s_nop 0
	global_load_lds_dwordx4 v147, s[52:53]
	s_mov_b32 m0, s44
	s_add_u32 s44, s52, 0x40000
	s_addc_u32 s45, s53, 0
	s_mov_b32 s95, m0
	s_mov_b32 m0, s61
	s_nop 0
	global_load_lds_dwordx4 v145, s[44:45]
	s_mov_b32 m0, s95
	s_nop 0
	s_mov_b32 s95, m0
	s_mov_b32 m0, s62
	s_nop 0
	global_load_lds_dwordx4 v147, s[44:45]
	s_mov_b32 m0, s95
	s_mov_b32 s44, m0
	s_mov_b32 m0, s40
	s_nop 0
	global_load_lds_dwordx4 v144, s[58:59]
	s_mov_b32 m0, s44
	s_nop 0
	s_mov_b32 s44, m0
	s_mov_b32 m0, s63
	s_nop 0
	global_load_lds_dwordx4 v146, s[58:59]
	s_mov_b32 m0, s44
	s_waitcnt vmcnt(8)
	s_waitcnt lgkmcnt(0)
	s_barrier
	s_setprio 1
	s_waitcnt lgkmcnt(7)
	v_mfma_f32_16x16x32_bf16 v[64:67], v[136:139], v[186:189], v[64:67]
	v_mfma_f32_16x16x32_bf16 v[60:63], v[154:157], v[186:189], v[60:63]
	s_waitcnt lgkmcnt(5)
	v_mfma_f32_16x16x32_bf16 v[48:51], v[136:139], v[194:197], v[48:51]
	v_mfma_f32_16x16x32_bf16 v[44:47], v[154:157], v[194:197], v[44:47]
	s_waitcnt lgkmcnt(3)
	v_mfma_f32_16x16x32_bf16 v[32:35], v[136:139], v[202:205], v[32:35]
	v_mfma_f32_16x16x32_bf16 v[28:31], v[154:157], v[202:205], v[28:31]
	s_waitcnt lgkmcnt(1)
	v_mfma_f32_16x16x32_bf16 v[16:19], v[136:139], v[210:213], v[16:19]
	v_mfma_f32_16x16x32_bf16 v[12:15], v[154:157], v[210:213], v[12:15]
	v_mfma_f32_16x16x32_bf16 v[64:67], v[140:143], v[190:193], v[64:67]
	v_mfma_f32_16x16x32_bf16 v[60:63], v[158:161], v[190:193], v[60:63]
	v_mfma_f32_16x16x32_bf16 v[48:51], v[140:143], v[198:201], v[48:51]
	v_mfma_f32_16x16x32_bf16 v[44:47], v[158:161], v[198:201], v[44:47]
	v_mfma_f32_16x16x32_bf16 v[32:35], v[140:143], v[206:209], v[32:35]
	v_mfma_f32_16x16x32_bf16 v[28:31], v[158:161], v[206:209], v[28:31]
	s_waitcnt lgkmcnt(0)
	v_mfma_f32_16x16x32_bf16 v[16:19], v[140:143], v[214:217], v[16:19]
	v_mfma_f32_16x16x32_bf16 v[12:15], v[158:161], v[214:217], v[12:15]
	s_setprio 0
	s_setprio 1
	v_mfma_f32_16x16x32_bf16 v[56:59], v[170:173], v[186:189], v[56:59]
	v_mfma_f32_16x16x32_bf16 v[52:55], v[178:181], v[186:189], v[52:55]
	v_mfma_f32_16x16x32_bf16 v[40:43], v[170:173], v[194:197], v[40:43]
	v_mfma_f32_16x16x32_bf16 v[36:39], v[178:181], v[194:197], v[36:39]
	v_mfma_f32_16x16x32_bf16 v[24:27], v[170:173], v[202:205], v[24:27]
	v_mfma_f32_16x16x32_bf16 v[20:23], v[178:181], v[202:205], v[20:23]
	v_mfma_f32_16x16x32_bf16 v[8:11], v[170:173], v[210:213], v[8:11]
	v_mfma_f32_16x16x32_bf16 v[2:5], v[178:181], v[210:213], v[4:7]
	v_mfma_f32_16x16x32_bf16 v[56:59], v[174:177], v[190:193], v[56:59]
	v_mfma_f32_16x16x32_bf16 v[52:55], v[182:185], v[190:193], v[52:55]
	v_mfma_f32_16x16x32_bf16 v[40:43], v[174:177], v[198:201], v[40:43]
	v_mfma_f32_16x16x32_bf16 v[36:39], v[182:185], v[198:201], v[36:39]
	v_mfma_f32_16x16x32_bf16 v[24:27], v[174:177], v[206:209], v[24:27]
	v_mfma_f32_16x16x32_bf16 v[20:23], v[182:185], v[206:209], v[20:23]
	v_mfma_f32_16x16x32_bf16 v[8:11], v[174:177], v[214:217], v[8:11]
	v_mfma_f32_16x16x32_bf16 v[2:5], v[182:185], v[214:217], v[2:5]
	s_setprio 0
	s_barrier
	v_add_u32_e32 v1, 0x18000, v152
	ds_read_b128 v[136:139], v1
	ds_read_b128 v[140:143], v1 offset:1024
	ds_read_b128 v[154:157], v1 offset:2048
	ds_read_b128 v[158:161], v1 offset:3072
	v_add_u32_e32 v1, 0x1c000, v152
	ds_read_b128 v[170:173], v1
	ds_read_b128 v[174:177], v1 offset:1024
	ds_read_b128 v[178:181], v1 offset:2048
	ds_read_b128 v[182:185], v1 offset:3072
	ds_read_b128 v[186:189], v153 offset:32768
	ds_read_b128 v[190:193], v153 offset:33792
	ds_read_b128 v[194:197], v153 offset:34816
	ds_read_b128 v[198:201], v153 offset:35840
	ds_read_b128 v[202:205], v153 offset:36864
	ds_read_b128 v[206:209], v153 offset:37888
	ds_read_b128 v[210:213], v153 offset:38912
	ds_read_b128 v[214:217], v153 offset:39936
	s_add_u32 s44, s58, 0x40000
	s_addc_u32 s45, s59, 0
	s_mov_b32 s58, m0
	s_mov_b32 m0, s64
	s_nop 0
	global_load_lds_dwordx4 v144, s[44:45]
	s_mov_b32 m0, s58
	s_nop 0
	s_mov_b32 s58, m0
	s_mov_b32 m0, s65
	s_nop 0
	global_load_lds_dwordx4 v146, s[44:45]
	s_mov_b32 m0, s58
	s_waitcnt vmcnt(8)
	s_waitcnt lgkmcnt(0)
	s_barrier
	s_setprio 1
	s_waitcnt lgkmcnt(7)
	v_mfma_f32_16x16x32_bf16 v[128:131], v[136:139], v[186:189], v[128:131]
	v_mfma_f32_16x16x32_bf16 v[124:127], v[154:157], v[186:189], v[124:127]
	s_waitcnt lgkmcnt(5)
	v_mfma_f32_16x16x32_bf16 v[112:115], v[136:139], v[194:197], v[112:115]
	v_mfma_f32_16x16x32_bf16 v[108:111], v[154:157], v[194:197], v[108:111]
	s_waitcnt lgkmcnt(3)
	v_mfma_f32_16x16x32_bf16 v[96:99], v[136:139], v[202:205], v[96:99]
	v_mfma_f32_16x16x32_bf16 v[92:95], v[154:157], v[202:205], v[92:95]
	s_waitcnt lgkmcnt(1)
	v_mfma_f32_16x16x32_bf16 v[80:83], v[136:139], v[210:213], v[80:83]
	v_mfma_f32_16x16x32_bf16 v[76:79], v[154:157], v[210:213], v[76:79]
	v_mfma_f32_16x16x32_bf16 v[128:131], v[140:143], v[190:193], v[128:131]
	v_mfma_f32_16x16x32_bf16 v[124:127], v[158:161], v[190:193], v[124:127]
	v_mfma_f32_16x16x32_bf16 v[112:115], v[140:143], v[198:201], v[112:115]
	v_mfma_f32_16x16x32_bf16 v[108:111], v[158:161], v[198:201], v[108:111]
	v_mfma_f32_16x16x32_bf16 v[96:99], v[140:143], v[206:209], v[96:99]
	v_mfma_f32_16x16x32_bf16 v[92:95], v[158:161], v[206:209], v[92:95]
	s_waitcnt lgkmcnt(0)
	v_mfma_f32_16x16x32_bf16 v[80:83], v[140:143], v[214:217], v[80:83]
	v_mfma_f32_16x16x32_bf16 v[76:79], v[158:161], v[214:217], v[76:79]
	s_setprio 0
	s_setprio 1
	v_mfma_f32_16x16x32_bf16 v[120:123], v[170:173], v[186:189], v[120:123]
	v_mfma_f32_16x16x32_bf16 v[116:119], v[178:181], v[186:189], v[116:119]
	v_mfma_f32_16x16x32_bf16 v[104:107], v[170:173], v[194:197], v[104:107]
	v_mfma_f32_16x16x32_bf16 v[100:103], v[178:181], v[194:197], v[100:103]
	v_mfma_f32_16x16x32_bf16 v[88:91], v[170:173], v[202:205], v[88:91]
	v_mfma_f32_16x16x32_bf16 v[84:87], v[178:181], v[202:205], v[84:87]
	v_mfma_f32_16x16x32_bf16 v[72:75], v[170:173], v[210:213], v[72:75]
	v_mfma_f32_16x16x32_bf16 v[68:71], v[178:181], v[210:213], v[68:71]
	v_mfma_f32_16x16x32_bf16 v[120:123], v[174:177], v[190:193], v[120:123]
	v_mfma_f32_16x16x32_bf16 v[116:119], v[182:185], v[190:193], v[116:119]
	v_mfma_f32_16x16x32_bf16 v[104:107], v[174:177], v[198:201], v[104:107]
	v_mfma_f32_16x16x32_bf16 v[100:103], v[182:185], v[198:201], v[100:103]
	v_mfma_f32_16x16x32_bf16 v[88:91], v[174:177], v[206:209], v[88:91]
	v_mfma_f32_16x16x32_bf16 v[84:87], v[182:185], v[206:209], v[84:87]
	v_mfma_f32_16x16x32_bf16 v[72:75], v[174:177], v[214:217], v[72:75]
	v_mfma_f32_16x16x32_bf16 v[68:71], v[182:185], v[214:217], v[68:71]
	s_setprio 0
	s_barrier
	ds_read_b128 v[186:189], v153 offset:49152
	ds_read_b128 v[190:193], v153 offset:50176
	ds_read_b128 v[194:197], v153 offset:51200
	ds_read_b128 v[198:201], v153 offset:52224
	ds_read_b128 v[202:205], v153 offset:53248
	ds_read_b128 v[206:209], v153 offset:54272
	ds_read_b128 v[210:213], v153 offset:55296
	ds_read_b128 v[214:217], v153 offset:56320
	s_mov_b32 s44, m0
	s_mov_b32 m0, s68
	s_nop 0
	global_load_lds_dwordx4 v145, s[56:57]
	s_mov_b32 m0, s44
	s_nop 0
	s_mov_b32 s44, m0
	s_mov_b32 m0, s69
	s_nop 0
	global_load_lds_dwordx4 v147, s[56:57]
	s_mov_b32 m0, s44
	s_add_u32 s44, s52, 0x40080
	s_addc_u32 s45, s53, 0
	s_mov_b32 s52, m0
	s_mov_b32 m0, s76
	s_nop 0
	global_load_lds_dwordx4 v145, s[44:45]
	s_mov_b32 m0, s52
	s_nop 0
	s_mov_b32 s52, m0
	s_mov_b32 m0, s77
	s_nop 0
	global_load_lds_dwordx4 v147, s[44:45]
	s_mov_b32 m0, s52
	s_mov_b32 s44, m0
	s_mov_b32 m0, s70
	s_nop 0
	global_load_lds_dwordx4 v144, s[54:55]
	s_mov_b32 m0, s44
	s_nop 0
	s_mov_b32 s44, m0
	s_mov_b32 m0, s71
	s_nop 0
	global_load_lds_dwordx4 v146, s[54:55]
	s_mov_b32 m0, s44
	s_waitcnt vmcnt(8)
	s_waitcnt lgkmcnt(0)
	s_barrier
	s_setprio 1
	s_waitcnt lgkmcnt(7)
	v_mfma_f32_16x16x32_bf16 v[64:67], v[136:139], v[186:189], v[64:67]
	v_mfma_f32_16x16x32_bf16 v[60:63], v[154:157], v[186:189], v[60:63]
	s_waitcnt lgkmcnt(5)
	v_mfma_f32_16x16x32_bf16 v[48:51], v[136:139], v[194:197], v[48:51]
	v_mfma_f32_16x16x32_bf16 v[44:47], v[154:157], v[194:197], v[44:47]
	s_waitcnt lgkmcnt(3)
	v_mfma_f32_16x16x32_bf16 v[32:35], v[136:139], v[202:205], v[32:35]
	v_mfma_f32_16x16x32_bf16 v[28:31], v[154:157], v[202:205], v[28:31]
	s_waitcnt lgkmcnt(1)
	v_mfma_f32_16x16x32_bf16 v[16:19], v[136:139], v[210:213], v[16:19]
	v_mfma_f32_16x16x32_bf16 v[12:15], v[154:157], v[210:213], v[12:15]
	v_mfma_f32_16x16x32_bf16 v[64:67], v[140:143], v[190:193], v[64:67]
	v_mfma_f32_16x16x32_bf16 v[60:63], v[158:161], v[190:193], v[60:63]
	v_mfma_f32_16x16x32_bf16 v[48:51], v[140:143], v[198:201], v[48:51]
	v_mfma_f32_16x16x32_bf16 v[44:47], v[158:161], v[198:201], v[44:47]
	v_mfma_f32_16x16x32_bf16 v[32:35], v[140:143], v[206:209], v[32:35]
	v_mfma_f32_16x16x32_bf16 v[28:31], v[158:161], v[206:209], v[28:31]
	s_waitcnt lgkmcnt(0)
	v_mfma_f32_16x16x32_bf16 v[16:19], v[140:143], v[214:217], v[16:19]
	v_mfma_f32_16x16x32_bf16 v[12:15], v[158:161], v[214:217], v[12:15]
	s_setprio 0
	s_setprio 1
	v_mfma_f32_16x16x32_bf16 v[56:59], v[170:173], v[186:189], v[56:59]
	v_mfma_f32_16x16x32_bf16 v[52:55], v[178:181], v[186:189], v[52:55]
	v_mfma_f32_16x16x32_bf16 v[40:43], v[170:173], v[194:197], v[40:43]
	v_mfma_f32_16x16x32_bf16 v[36:39], v[178:181], v[194:197], v[36:39]
	v_mfma_f32_16x16x32_bf16 v[24:27], v[170:173], v[202:205], v[24:27]
	v_mfma_f32_16x16x32_bf16 v[20:23], v[178:181], v[202:205], v[20:23]
	v_mfma_f32_16x16x32_bf16 v[6:9], v[170:173], v[210:213], v[8:11]
	v_mfma_f32_16x16x32_bf16 v[2:5], v[178:181], v[210:213], v[2:5]
	v_mfma_f32_16x16x32_bf16 v[56:59], v[174:177], v[190:193], v[56:59]
	v_mfma_f32_16x16x32_bf16 v[52:55], v[182:185], v[190:193], v[52:55]
	v_mfma_f32_16x16x32_bf16 v[40:43], v[174:177], v[198:201], v[40:43]
	v_mfma_f32_16x16x32_bf16 v[36:39], v[182:185], v[198:201], v[36:39]
	v_mfma_f32_16x16x32_bf16 v[24:27], v[174:177], v[206:209], v[24:27]
	v_mfma_f32_16x16x32_bf16 v[20:23], v[182:185], v[206:209], v[20:23]
	v_mfma_f32_16x16x32_bf16 v[8:11], v[174:177], v[214:217], v[6:9]
	v_mfma_f32_16x16x32_bf16 v[4:7], v[182:185], v[214:217], v[2:5]
	s_setprio 0
	s_barrier
	s_add_i32 s94, s94, 2
	s_add_u32 s92, s92, 0x100
	s_addc_u32 s93, s93, 0
	s_cmp_gt_u32 s94, 13
	s_cbranch_scc1 .LBB0_492
	s_mov_b64 s[44:45], s[50:51]
	s_cmp_lg_u32 s94, 6
	s_cbranch_scc0 .LBB0_489
	s_branch .LBB0_490
